# v23 + next tile's first QK MFMA issued before the row-sum finalize chain at the first tile-step boundary (A and B)
# baseline (speedup 1.0000x reference)
; template <int DK, bool NOMAX> ...
;     ...
;   for (int i = 0; i < 16; ++i) {
;     if (i + 2 < 16) VRD_((i + 2) % 3, i + 2);
;     if (i == 1) { if (dk) __builtin_amdgcn_global_load_lds((const unsigned*)gk0, lk, 16, 0, 0); }
;     if (i == 3) { if constexpr (DK == 128) { if (dk) __builtin_amdgcn_global_load_lds((const unsigned*)gk1, (lds_up)((lds_cp)lk + 8192), 16, 0, 0); } }
;     if (i == 5) { if (dv) __builtin_amdgcn_global_load_lds((const unsigned*)gv0, lv, 16, 0, 0); }
;     if (i == 7) { if (dv) __builtin_amdgcn_global_load_lds((const unsigned*)gv1, (lds_up)((lds_cp)lv + 8192), 16, 0, 0); }
;     if (i == 12 || i == 13) { const int cb_ = ((i - 12) * 16 + hi * 8) * 2;
;       if constexpr (DK == 128) { kf[i - 12][0] = *reinterpret_cast<const bf16x8*>(Kn + KSWZ128(r32, cb_)); kf[i - 12][1] = *reinterpret_cast<const bf16x8*>(Kn + KSWZ128(32 + r32, cb_)); }
;       else { kf[i - 12][0] = *reinterpret_cast<const bf16x8*>(Kn + KSWZ64(r32, cb_)); kf[i - 12][1] = *reinterpret_cast<const bf16x8*>(Kn + KSWZ64(32 + r32, cb_)); } }
;     SBAR();
;     o[i & 3] = __builtin_amdgcn_mfma_f32_32x32x16_bf16(pa[i >> 2], VFR_(i % 3), o[i & 3], 0, 0, 0);
;     if constexpr (NOMAX) { c0[i] = __builtin_amdgcn_exp2f(c0[i]); c1[i] = __builtin_amdgcn_exp2f(c1[i]); if (i > 0) { psa += c0[i - 1]; psb += c1[i - 1]; } PIN(c0); PIN(c1); PIN(psa); PIN(psb); }
;     else {
;     if (i == 0) { ma = max3f(c0[0], c0[1], c1[0]); mb = max3f(c0[2], c0[3], c1[1]); ma = max3f(ma, c1[2], c1[3]); }
;     if (i >= 1 && i <= 3) { const int r = 4 * i; ma = max3f(ma, c0[r], c0[r + 1]); mb = max3f(mb, c0[r + 2], c0[r + 3]); ma = max3f(ma, c1[r], c1[r + 1]); mb = max3f(mb, c1[r + 2], c1[r + 3]); }
;     if (i == 4) { float pmax = fmaxf(ma, mb);
;       { auto rr = __builtin_amdgcn_permlane32_swap(__float_as_uint(pmax), __float_as_uint(pmax), false, false);
;         pmax = fmaxf(__uint_as_float(rr[0]), __uint_as_float(rr[1])); }
;       pmax += cb;
;       const bool keep = __all(pmax - m_reg <= THR2);
;       const float mn = keep ? m_reg : fmaxf(m_reg, pmax);
;       alpha = __builtin_amdgcn_exp2f(m_reg - mn); m_reg = mn; mnC = cb - mn; }
;     if (i >= 5 && i <= 8) { const int r = 4 * (i - 5);
; #pragma unroll
;       for (int q = 0; q < 4; ++q) { c0[r + q] += mnC; c1[r + q] += mnC; } }
;     if (i >= 9) { const int r0 = (i - 9) * 2 + (i > 14 ? 1 : 0), n = i >= 14 ? 3 : 2;
; #pragma unroll
.LBB0_226:
	v_sub_f32_e32 v0, v212, v215
	v_exp_f32_e32 v0, v0
	s_add_i32 s4, s63, 0xffff8000
	s_and_b32 s4, s4, 0xc000
	s_add_i32 s94, s4, 0
	s_waitcnt lgkmcnt(4)
	v_mfma_f32_32x32x16_bf16 v[32:47], v[96:99], v[100:103], v[32:47]
	v_exp_f32_e32 v129, v129
	v_exp_f32_e32 v113, v113
	ds_read_b64_tr_b16 v[88:89], v213 offset:4096
	ds_read_b64_tr_b16 v[90:91], v213 offset:6144
	s_waitcnt lgkmcnt(4)
	v_mfma_f32_32x32x16_bf16 v[48:63], v[96:99], v[80:83], v[48:63]
	v_exp_f32_e32 v130, v130
	v_exp_f32_e32 v114, v114
	v_add_f32_e32 v100, v113, v112
	v_add_f32_e32 v101, v129, v128
	ds_read_b64_tr_b16 v[80:81], v213 offset:4608
	ds_read_b64_tr_b16 v[82:83], v213 offset:6656
	s_waitcnt lgkmcnt(4)
	v_mfma_f32_32x32x16_bf16 v[64:79], v[96:99], v[84:87], v[64:79]
	v_exp_f32_e32 v131, v131
	v_exp_f32_e32 v115, v115
	v_add_f32_e32 v96, v114, v100
	v_add_f32_e32 v97, v130, v101
	ds_read_b64_tr_b16 v[84:85], v213 offset:5120
	ds_read_b64_tr_b16 v[86:87], v213 offset:7168
	s_waitcnt lgkmcnt(4)
	v_mfma_f32_32x32x16_bf16 v[16:31], v[10:13], v[88:91], v[16:31]
	v_exp_f32_e32 v132, v132
	v_exp_f32_e32 v116, v116
	v_add_f32_e32 v96, v115, v96
	v_add_f32_e32 v97, v131, v97
	s_add_u32 vcc_lo, s0, s30
	s_addc_u32 vcc_hi, s1, s31
	s_add_i32 s4, s62, s58
	s_mov_b32 m0, s4
	ds_read_b64_tr_b16 v[88:89], v213 offset:5632
	ds_read_b64_tr_b16 v[90:91], v213 offset:7680
	global_load_lds_dwordx4 v160, vcc
	s_waitcnt lgkmcnt(4)
	v_mfma_f32_32x32x16_bf16 v[32:47], v[10:13], v[80:83], v[32:47]
	v_exp_f32_e32 v133, v133
	v_exp_f32_e32 v117, v117
	v_add_f32_e32 v92, v116, v96
	v_add_f32_e32 v93, v132, v97
	ds_read_b64_tr_b16 v[80:81], v213 offset:8192
	ds_read_b64_tr_b16 v[82:83], v213 offset:10240
	s_waitcnt lgkmcnt(4)
	v_mfma_f32_32x32x16_bf16 v[48:63], v[10:13], v[84:87], v[48:63]
	v_exp_f32_e32 v134, v134
	v_exp_f32_e32 v118, v118
	v_add_f32_e32 v92, v117, v92
	v_add_f32_e32 v93, v133, v93
	s_add_i32 m0, s4, 0x2000
	ds_read_b64_tr_b16 v[84:85], v213 offset:8704
	ds_read_b64_tr_b16 v[86:87], v213 offset:10752
	global_load_lds_dwordx4 v14, vcc
	s_waitcnt lgkmcnt(4)
	v_mfma_f32_32x32x16_bf16 v[64:79], v[10:13], v[88:91], v[64:79]
	v_exp_f32_e32 v135, v135
	v_exp_f32_e32 v119, v119
	v_add_f32_e32 v88, v118, v92
	v_add_f32_e32 v89, v134, v93
	ds_read_b64_tr_b16 v[10:11], v213 offset:9216
	ds_read_b64_tr_b16 v[12:13], v213 offset:11264
	s_waitcnt lgkmcnt(4)
	v_mfma_f32_32x32x16_bf16 v[16:31], v[6:9], v[80:83], v[16:31]
	v_exp_f32_e32 v136, v136
	v_exp_f32_e32 v120, v120
	v_add_f32_e32 v88, v119, v88
	v_add_f32_e32 v89, v135, v89
	ds_read_b64_tr_b16 v[80:81], v213 offset:9728
	ds_read_b64_tr_b16 v[82:83], v213 offset:11776
	s_waitcnt lgkmcnt(4)
	v_mfma_f32_32x32x16_bf16 v[32:47], v[6:9], v[84:87], v[32:47]
	v_exp_f32_e32 v137, v137
	v_exp_f32_e32 v121, v121
	v_add_f32_e32 v84, v120, v88
	v_add_f32_e32 v85, v136, v89
	ds_read_b64_tr_b16 v[88:89], v213 offset:12288
	ds_read_b64_tr_b16 v[90:91], v213 offset:14336
	s_waitcnt lgkmcnt(4)
	v_mfma_f32_32x32x16_bf16 v[48:63], v[6:9], v[10:13], v[48:63]
	v_exp_f32_e32 v138, v138
	v_exp_f32_e32 v122, v122
	v_add_f32_e32 v10, v121, v84
	v_add_f32_e32 v11, v137, v85
	ds_read_b64_tr_b16 v[92:93], v213 offset:12800
	ds_read_b64_tr_b16 v[94:95], v213 offset:14848
	s_waitcnt lgkmcnt(4)
	v_mfma_f32_32x32x16_bf16 v[64:79], v[6:9], v[80:83], v[64:79]
	v_exp_f32_e32 v139, v139
	v_exp_f32_e32 v123, v123
	v_add_f32_e32 v6, v122, v10
	v_add_f32_e32 v7, v138, v11
	v_add_u32_e32 v8, s94, v209
	ds_read_b64_tr_b16 v[96:97], v213 offset:13312
	ds_read_b64_tr_b16 v[98:99], v213 offset:15360
	ds_read_b128 v[80:83], v8
	ds_read_b128 v[84:87], v8 offset:4096
	s_waitcnt lgkmcnt(6)
	v_mfma_f32_32x32x16_bf16 v[16:31], v[2:5], v[88:91], v[16:31]
	v_exp_f32_e32 v140, v140
	v_exp_f32_e32 v124, v124
	v_add_f32_e32 v100, v123, v6
	v_add_f32_e32 v101, v139, v7
	v_add_u32_e32 v10, s94, v210
	ds_read_b64_tr_b16 v[88:89], v213 offset:13824
	ds_read_b64_tr_b16 v[90:91], v213 offset:15872
	ds_read_b128 v[6:9], v10
	ds_read_b128 v[10:13], v10 offset:4096
	s_waitcnt lgkmcnt(8)
	v_mfma_f32_32x32x16_bf16 v[32:47], v[2:5], v[92:95], v[32:47]
	v_exp_f32_e32 v141, v141
	v_exp_f32_e32 v125, v125
	v_add_f32_e32 v92, v124, v100
	v_add_f32_e32 v93, v140, v101
	s_waitcnt lgkmcnt(6)
	v_mfma_f32_32x32x16_bf16 v[48:63], v[2:5], v[96:99], v[48:63]
	v_exp_f32_e32 v142, v142
	v_exp_f32_e32 v126, v126
	v_add_f32_e32 v92, v125, v92
	v_add_f32_e32 v93, v141, v93
	s_waitcnt lgkmcnt(2)
	v_mfma_f32_32x32x16_bf16 v[64:79], v[2:5], v[88:91], v[64:79]
	v_exp_f32_e32 v143, v143
	v_exp_f32_e32 v127, v127
	v_add_f32_e32 v2, v126, v92
	v_add_f32_e32 v3, v142, v93
	v_cmp_neq_f32_e32 vcc, 1.0, v0
	s_cbranch_vccnz .Lmy_resc_a1_1
	s_waitcnt lgkmcnt(0)
	v_add_u32_e32 v217, s6, v187
	v_mfma_f32_32x32x16_bf16 v[96:111], v[80:83], v[156:159], 0
	s_nop 0
	v_add_f32_e32 v3, v143, v3
	v_add_f32_e32 v2, v127, v2
	v_add_f32_e32 v213, v3, v2
	v_mov_b32_e32 v214, v213
	s_nop 1
	v_permlane32_swap_b32_e32 v213, v214

; #define SBAR() __builtin_amdgcn_sched_barrier(0)
; __device__ __forceinline__ s16x4 vtr(lds_cptr p) { return __builtin_bit_cast(s16x4, __builtin_amdgcn_ds_read_tr16_b64_v4i16((__attribute__((address_space(3))) v4i16_t*)p)); }
; #define PIN(x) asm volatile("" : "+v"(x))
; template <int DK, bool NOMAX> ...
;     ...
;   float psa = 0.f, psb = 0.f;
;   SBAR();
; #pragma unroll
;   for (int d0 = 0; d0 < NS; ++d0) {
;     if (d0 == 0) { c0 = __builtin_amdgcn_mfma_f32_32x32x16_bf16(kf[0][0], qr[0], f32x16{}, 0, 0, 0); c1 = __builtin_amdgcn_mfma_f32_32x32x16_bf16(kf[0][1], qr[0], f32x16{}, 0, 0, 0); }
;     else { c0 = __builtin_amdgcn_mfma_f32_32x32x16_bf16(kf[d0 & 1][0], qr[d0], c0, 0, 0, 0); c1 = __builtin_amdgcn_mfma_f32_32x32x16_bf16(kf[d0 & 1][1], qr[d0], c1, 0, 0, 0); }
;     if (d0 + 2 < NS) KRD_(d0 & 1, d0 + 2);
;     if constexpr (NOMAX) { }
;     else {
; #pragma unroll
;     for (int r = d0 * RPS; r < (d0 + 1) * RPS; ++r) { p1[r] = __builtin_amdgcn_exp2f(p1[r]); psa += p0[r]; }
;     if (d0 > 0) {
; #pragma unroll
;       for (int r = (d0 - 1) * RPS; r < d0 * RPS; ++r) psb += p1[r]; } }
;     if constexpr (NOMAX) {
;       if (d0 == NS / 4 - 1) { PK4R(p0, 0, pa[0]); PIN(pa[0]); }
;       if (d0 == NS / 2 - 1) { PK4R(p0, 8, pa[1]); PIN(pa[1]); }
;       if (d0 == 3 * NS / 4 - 1) { PK4R(p1, 0, pa[2]); PIN(pa[2]); }
;       if (d0 == NS - 1) { PK4R(p1, 8, pa[3]); PIN(pa[3]); }
;     } else {
;     if (d0 == NS / 2 - 1) { PK4R(p0, 0, pa[0]); PIN(pa[0]); }
;     if (d0 == NS / 2) { PK4R(p0, 8, pa[1]); PIN(pa[1]); }
;     if (d0 == NS - 1) { PK4R(p1, 0, pa[2]); PIN(pa[2]); }
;     }
;     if (d0 == NS - 1) {
;       vl[0] = vtr(vp + v_rd_off(0, 0, 0)); vh[0] = vtr(vp + v_rd_off(0, 0, 1)); vl[1] = vtr(vp + v_rd_off(1, 0, 0)); vh[1] = vtr(vp + v_rd_off(1, 0, 1)); }
;     PIN(p1); PIN(psa); PIN(psb);
;     SBAR();
;   }
.LBB0_232:
.LBB0_234:
	v_add_u32_e32 v212, s94, v207
	ds_read_b128 v[2:5], v212
	ds_read_b128 v[218:221], v212 offset:4096
	v_cvt_pk_bf16_f32 v128, v128, v129
	v_cvt_pk_bf16_f32 v129, v130, v131
	v_cvt_pk_bf16_f32 v130, v132, v133
	v_cvt_pk_bf16_f32 v131, v134, v135
	v_mfma_f32_32x32x16_bf16 v[80:95], v[84:87], v[156:159], 0
	v_permlane32_swap_b32_e32 v128, v130
	v_permlane32_swap_b32_e32 v129, v131
	v_mfma_f32_32x32x16_bf16 v[96:111], v[6:9], v[152:155], v[96:111]
	v_add_u32_e32 v6, s94, v208
	ds_read_b128 v[132:135], v6
	ds_read_b128 v[222:225], v6 offset:4096
	v_mfma_f32_32x32x16_bf16 v[80:95], v[10:13], v[152:155], v[80:95]
	v_cvt_pk_bf16_f32 v10, v136, v137
	v_cvt_pk_bf16_f32 v11, v138, v139
	v_cvt_pk_bf16_f32 v12, v140, v141
	v_cvt_pk_bf16_f32 v13, v142, v143
	s_nop 0
	v_permlane32_swap_b32_e32 v10, v12
	v_permlane32_swap_b32_e32 v11, v13
	s_waitcnt lgkmcnt(3)
	v_mfma_f32_32x32x16_bf16 v[96:111], v[2:5], v[148:151], v[96:111]
	v_cvt_pk_bf16_f32 v6, v112, v113
	v_cvt_pk_bf16_f32 v7, v114, v115
	v_cvt_pk_bf16_f32 v8, v116, v117
	v_cvt_pk_bf16_f32 v9, v118, v119
	s_nop 0
	v_permlane32_swap_b32_e32 v6, v8
	s_waitcnt lgkmcnt(2)
	v_mfma_f32_32x32x16_bf16 v[80:95], v[218:221], v[148:151], v[80:95]
	v_permlane32_swap_b32_e32 v7, v9
	s_nop 0
	v_cvt_pk_bf16_f32 v2, v120, v121
	v_cvt_pk_bf16_f32 v3, v122, v123
	v_cvt_pk_bf16_f32 v4, v124, v125
	v_cvt_pk_bf16_f32 v5, v126, v127
	s_waitcnt lgkmcnt(1)
	v_mfma_f32_32x32x16_bf16 v[96:111], v[132:135], v[144:147], v[96:111]
	v_permlane32_swap_b32_e32 v2, v4
	v_permlane32_swap_b32_e32 v3, v5
	s_cmpk_gt_i32 s97, 0x7c
	s_cbranch_scc1 .Lmy_mb0_a1_2
	s_waitcnt vmcnt(3) lgkmcnt(0)
	s_barrier

; template <int DK, bool NOMAX> ...
;     ...
;   if constexpr (NOMAX) { float ps = (psa + c0[15]) + (psb + c1[15]);
;     { auto rr = __builtin_amdgcn_permlane32_swap(__float_as_uint(ps), __float_as_uint(ps), false, false);
;       ps = __uint_as_float(rr[0]) + __uint_as_float(rr[1]); }
;     l_reg = l_reg * alpha + ps; }
.Lmy_resc_a1_1:
	s_nop 0
	v_add_f32_e32 v3, v143, v3
	v_add_f32_e32 v2, v127, v2
	v_add_f32_e32 v213, v3, v2
	v_mov_b32_e32 v214, v213
	s_nop 1
	v_permlane32_swap_b32_e32 v213, v214
	s_and_saveexec_b64 s[4:5], s[46:47]
	ds_write_b32 v188, v0 offset:128
	s_or_b64 exec, exec, s[4:5]
	s_waitcnt lgkmcnt(0)
	v_add_u32_e32 v96, s2, v171
	ds_read_b128 v[2:5], v96 offset:224
	ds_read_b128 v[88:91], v96 offset:192
	ds_read_b128 v[92:95], v96 offset:160
	ds_read_b128 v[96:99], v96 offset:128
	s_waitcnt lgkmcnt(0)
	v_pk_mul_f32 v[28:29], v[28:29], v[2:3]
	v_pk_mul_f32 v[24:25], v[24:25], v[88:89]
	v_pk_mul_f32 v[20:21], v[20:21], v[92:93]
	v_pk_mul_f32 v[30:31], v[30:31], v[4:5]
	v_pk_mul_f32 v[26:27], v[26:27], v[90:91]
	v_pk_mul_f32 v[22:23], v[22:23], v[94:95]
	v_pk_mul_f32 v[18:19], v[18:19], v[98:99]
	v_pk_mul_f32 v[16:17], v[16:17], v[96:97]
	v_pk_mul_f32 v[44:45], v[44:45], v[2:3]
	v_pk_mul_f32 v[40:41], v[40:41], v[88:89]
	v_pk_mul_f32 v[36:37], v[36:37], v[92:93]
	v_pk_mul_f32 v[46:47], v[46:47], v[4:5]
	v_pk_mul_f32 v[42:43], v[42:43], v[90:91]
	v_pk_mul_f32 v[38:39], v[38:39], v[94:95]
	v_pk_mul_f32 v[34:35], v[34:35], v[98:99]
	v_pk_mul_f32 v[32:33], v[32:33], v[96:97]
	v_pk_mul_f32 v[60:61], v[60:61], v[2:3]
	v_pk_mul_f32 v[56:57], v[56:57], v[88:89]
	v_pk_mul_f32 v[52:53], v[52:53], v[92:93]
	v_pk_mul_f32 v[62:63], v[62:63], v[4:5]
	v_pk_mul_f32 v[58:59], v[58:59], v[90:91]
	v_pk_mul_f32 v[54:55], v[54:55], v[94:95]
	v_pk_mul_f32 v[50:51], v[50:51], v[98:99]
	v_pk_mul_f32 v[48:49], v[48:49], v[96:97]
	v_pk_mul_f32 v[76:77], v[76:77], v[2:3]
	v_pk_mul_f32 v[72:73], v[72:73], v[88:89]
	v_pk_mul_f32 v[68:69], v[68:69], v[92:93]
	v_pk_mul_f32 v[78:79], v[78:79], v[4:5]
	v_pk_mul_f32 v[74:75], v[74:75], v[90:91]
	v_pk_mul_f32 v[70:71], v[70:71], v[94:95]
	v_pk_mul_f32 v[66:67], v[66:67], v[98:99]
	v_pk_mul_f32 v[64:65], v[64:65], v[96:97]
	s_waitcnt lgkmcnt(0)
	v_add_u32_e32 v217, s6, v187
	v_mfma_f32_32x32x16_bf16 v[96:111], v[80:83], v[156:159], 0
	s_branch .LBB0_230

; template <int DK, bool NOMAX> ...
;     ...
;   for (int i = 0; i < 16; ++i) {
;     if (i + 2 < 16) VRD_((i + 2) % 3, i + 2);
;     if (i == 1) { if (dk) __builtin_amdgcn_global_load_lds((const unsigned*)gk0, lk, 16, 0, 0); }
;     if (i == 3) { if constexpr (DK == 128) { if (dk) __builtin_amdgcn_global_load_lds((const unsigned*)gk1, (lds_up)((lds_cp)lk + 8192), 16, 0, 0); } }
;     if (i == 5) { if (dv) __builtin_amdgcn_global_load_lds((const unsigned*)gv0, lv, 16, 0, 0); }
;     if (i == 7) { if (dv) __builtin_amdgcn_global_load_lds((const unsigned*)gv1, (lds_up)((lds_cp)lv + 8192), 16, 0, 0); }
;     if (i == 12 || i == 13) { const int cb_ = ((i - 12) * 16 + hi * 8) * 2;
;       if constexpr (DK == 128) { kf[i - 12][0] = *reinterpret_cast<const bf16x8*>(Kn + KSWZ128(r32, cb_)); kf[i - 12][1] = *reinterpret_cast<const bf16x8*>(Kn + KSWZ128(32 + r32, cb_)); }
;       else { kf[i - 12][0] = *reinterpret_cast<const bf16x8*>(Kn + KSWZ64(r32, cb_)); kf[i - 12][1] = *reinterpret_cast<const bf16x8*>(Kn + KSWZ64(32 + r32, cb_)); } }
;     SBAR();
;     o[i & 3] = __builtin_amdgcn_mfma_f32_32x32x16_bf16(pa[i >> 2], VFR_(i % 3), o[i & 3], 0, 0, 0);
;     if constexpr (NOMAX) { c0[i] = __builtin_amdgcn_exp2f(c0[i]); c1[i] = __builtin_amdgcn_exp2f(c1[i]); if (i > 0) { psa += c0[i - 1]; psb += c1[i - 1]; } PIN(c0); PIN(c1); PIN(psa); PIN(psb); }
;     else {
;     if (i == 0) { ma = max3f(c0[0], c0[1], c1[0]); mb = max3f(c0[2], c0[3], c1[1]); ma = max3f(ma, c1[2], c1[3]); }
;     if (i >= 1 && i <= 3) { const int r = 4 * i; ma = max3f(ma, c0[r], c0[r + 1]); mb = max3f(mb, c0[r + 2], c0[r + 3]); ma = max3f(ma, c1[r], c1[r + 1]); mb = max3f(mb, c1[r + 2], c1[r + 3]); }
;     if (i == 4) { float pmax = fmaxf(ma, mb);
;       { auto rr = __builtin_amdgcn_permlane32_swap(__float_as_uint(pmax), __float_as_uint(pmax), false, false);
;         pmax = fmaxf(__uint_as_float(rr[0]), __uint_as_float(rr[1])); }
;       pmax += cb;
;       const bool keep = __all(pmax - m_reg <= THR2);
;       const float mn = keep ? m_reg : fmaxf(m_reg, pmax);
;       alpha = __builtin_amdgcn_exp2f(m_reg - mn); m_reg = mn; mnC = cb - mn; }
;     if (i >= 5 && i <= 8) { const int r = 4 * (i - 5);
; #pragma unroll
;       for (int q = 0; q < 4; ++q) { c0[r + q] += mnC; c1[r + q] += mnC; } }
;     if (i >= 9) { const int r0 = (i - 9) * 2 + (i > 14 ? 1 : 0), n = i >= 14 ? 3 : 2;
; #pragma unroll
.LBB0_319:
	v_sub_f32_e32 v0, v212, v215
	v_exp_f32_e32 v0, v0
	s_add_i32 s4, s63, 0xffff8000
	s_and_b32 s4, s4, 0xc000
	s_add_i32 s18, s4, 0
	s_waitcnt lgkmcnt(4)
	v_mfma_f32_32x32x16_bf16 v[32:47], v[96:99], v[100:103], v[32:47]
	v_exp_f32_e32 v129, v129
	v_exp_f32_e32 v113, v113
	ds_read_b64_tr_b16 v[88:89], v213 offset:4096
	ds_read_b64_tr_b16 v[90:91], v213 offset:6144
	s_waitcnt lgkmcnt(4)
	v_mfma_f32_32x32x16_bf16 v[48:63], v[96:99], v[80:83], v[48:63]
	v_exp_f32_e32 v130, v130
	v_exp_f32_e32 v114, v114
	v_add_f32_e32 v100, v113, v112
	v_add_f32_e32 v101, v129, v128
	ds_read_b64_tr_b16 v[80:81], v213 offset:4608
	ds_read_b64_tr_b16 v[82:83], v213 offset:6656
	s_waitcnt lgkmcnt(4)
	v_mfma_f32_32x32x16_bf16 v[64:79], v[96:99], v[84:87], v[64:79]
	v_exp_f32_e32 v131, v131
	v_exp_f32_e32 v115, v115
	v_add_f32_e32 v96, v114, v100
	v_add_f32_e32 v97, v130, v101
	ds_read_b64_tr_b16 v[84:85], v213 offset:5120
	ds_read_b64_tr_b16 v[86:87], v213 offset:7168
	s_waitcnt lgkmcnt(4)
	v_mfma_f32_32x32x16_bf16 v[16:31], v[10:13], v[88:91], v[16:31]
	v_exp_f32_e32 v132, v132
	v_exp_f32_e32 v116, v116
	v_add_f32_e32 v96, v115, v96
	v_add_f32_e32 v97, v131, v97
	s_add_u32 vcc_lo, s0, s30
	s_addc_u32 vcc_hi, s1, s31
	s_add_i32 s4, s62, s97
	s_mov_b32 m0, s4
	ds_read_b64_tr_b16 v[88:89], v213 offset:5632
	ds_read_b64_tr_b16 v[90:91], v213 offset:7680
	global_load_lds_dwordx4 v160, vcc
	s_waitcnt lgkmcnt(4)
	v_mfma_f32_32x32x16_bf16 v[32:47], v[10:13], v[80:83], v[32:47]
	v_exp_f32_e32 v133, v133
	v_exp_f32_e32 v117, v117
	v_add_f32_e32 v92, v116, v96
	v_add_f32_e32 v93, v132, v97
	ds_read_b64_tr_b16 v[80:81], v213 offset:8192
	ds_read_b64_tr_b16 v[82:83], v213 offset:10240
	s_waitcnt lgkmcnt(4)
	v_mfma_f32_32x32x16_bf16 v[48:63], v[10:13], v[84:87], v[48:63]
	v_exp_f32_e32 v134, v134
	v_exp_f32_e32 v118, v118
	v_add_f32_e32 v92, v117, v92
	v_add_f32_e32 v93, v133, v93
	s_add_i32 m0, s4, 0x2000
	ds_read_b64_tr_b16 v[84:85], v213 offset:8704
	ds_read_b64_tr_b16 v[86:87], v213 offset:10752
	global_load_lds_dwordx4 v14, vcc
	s_waitcnt lgkmcnt(4)
	v_mfma_f32_32x32x16_bf16 v[64:79], v[10:13], v[88:91], v[64:79]
	v_exp_f32_e32 v135, v135
	v_exp_f32_e32 v119, v119
	v_add_f32_e32 v88, v118, v92
	v_add_f32_e32 v89, v134, v93
	ds_read_b64_tr_b16 v[10:11], v213 offset:9216
	ds_read_b64_tr_b16 v[12:13], v213 offset:11264
	s_waitcnt lgkmcnt(4)
	v_mfma_f32_32x32x16_bf16 v[16:31], v[6:9], v[80:83], v[16:31]
	v_exp_f32_e32 v136, v136
	v_exp_f32_e32 v120, v120
	v_add_f32_e32 v88, v119, v88
	v_add_f32_e32 v89, v135, v89
	ds_read_b64_tr_b16 v[80:81], v213 offset:9728
	ds_read_b64_tr_b16 v[82:83], v213 offset:11776
	s_waitcnt lgkmcnt(4)
	v_mfma_f32_32x32x16_bf16 v[32:47], v[6:9], v[84:87], v[32:47]
	v_exp_f32_e32 v137, v137
	v_exp_f32_e32 v121, v121
	v_add_f32_e32 v84, v120, v88
	v_add_f32_e32 v85, v136, v89
	ds_read_b64_tr_b16 v[88:89], v213 offset:12288
	ds_read_b64_tr_b16 v[90:91], v213 offset:14336
	s_waitcnt lgkmcnt(4)
	v_mfma_f32_32x32x16_bf16 v[48:63], v[6:9], v[10:13], v[48:63]
	v_exp_f32_e32 v138, v138
	v_exp_f32_e32 v122, v122
	v_add_f32_e32 v10, v121, v84
	v_add_f32_e32 v11, v137, v85
	ds_read_b64_tr_b16 v[92:93], v213 offset:12800
	ds_read_b64_tr_b16 v[94:95], v213 offset:14848
	s_waitcnt lgkmcnt(4)
	v_mfma_f32_32x32x16_bf16 v[64:79], v[6:9], v[80:83], v[64:79]
	v_exp_f32_e32 v139, v139
	v_exp_f32_e32 v123, v123
	v_add_f32_e32 v6, v122, v10
	v_add_f32_e32 v7, v138, v11
	v_add_u32_e32 v8, s18, v209
	ds_read_b64_tr_b16 v[96:97], v213 offset:13312
	ds_read_b64_tr_b16 v[98:99], v213 offset:15360
	ds_read_b128 v[80:83], v8
	ds_read_b128 v[84:87], v8 offset:4096
	s_waitcnt lgkmcnt(6)
	v_mfma_f32_32x32x16_bf16 v[16:31], v[2:5], v[88:91], v[16:31]
	v_exp_f32_e32 v140, v140
	v_exp_f32_e32 v124, v124
	v_add_f32_e32 v100, v123, v6
	v_add_f32_e32 v101, v139, v7
	v_add_u32_e32 v10, s18, v210
	ds_read_b64_tr_b16 v[88:89], v213 offset:13824
	ds_read_b64_tr_b16 v[90:91], v213 offset:15872
	ds_read_b128 v[6:9], v10
	ds_read_b128 v[10:13], v10 offset:4096
	s_waitcnt lgkmcnt(8)
	v_mfma_f32_32x32x16_bf16 v[32:47], v[2:5], v[92:95], v[32:47]
	v_exp_f32_e32 v141, v141
	v_exp_f32_e32 v125, v125
	v_add_f32_e32 v92, v124, v100
	v_add_f32_e32 v93, v140, v101
	s_waitcnt lgkmcnt(6)
	v_mfma_f32_32x32x16_bf16 v[48:63], v[2:5], v[96:99], v[48:63]
	v_exp_f32_e32 v142, v142
	v_exp_f32_e32 v126, v126
	v_add_f32_e32 v92, v125, v92
	v_add_f32_e32 v93, v141, v93
	s_waitcnt lgkmcnt(2)
	v_mfma_f32_32x32x16_bf16 v[64:79], v[2:5], v[88:91], v[64:79]
	v_exp_f32_e32 v143, v143
	v_exp_f32_e32 v127, v127
	v_add_f32_e32 v2, v126, v92
	v_add_f32_e32 v3, v142, v93
	v_cmp_neq_f32_e32 vcc, 1.0, v0
	s_cbranch_vccnz .Lmy_resc_a2_1
	s_waitcnt lgkmcnt(0)
	v_add_u32_e32 v217, s58, v187
	v_mfma_f32_32x32x16_bf16 v[96:111], v[80:83], v[156:159], 0
	s_nop 0
	v_add_f32_e32 v3, v143, v3
	v_add_f32_e32 v2, v127, v2
	v_add_f32_e32 v213, v3, v2
	v_mov_b32_e32 v214, v213
	s_nop 1
	v_permlane32_swap_b32_e32 v213, v214

; #define SBAR() __builtin_amdgcn_sched_barrier(0)
; __device__ __forceinline__ s16x4 vtr(lds_cptr p) { return __builtin_bit_cast(s16x4, __builtin_amdgcn_ds_read_tr16_b64_v4i16((__attribute__((address_space(3))) v4i16_t*)p)); }
; #define PIN(x) asm volatile("" : "+v"(x))
; template <int DK, bool NOMAX> ...
;     ...
;   float psa = 0.f, psb = 0.f;
;   SBAR();
; #pragma unroll
;   for (int d0 = 0; d0 < NS; ++d0) {
;     if (d0 == 0) { c0 = __builtin_amdgcn_mfma_f32_32x32x16_bf16(kf[0][0], qr[0], f32x16{}, 0, 0, 0); c1 = __builtin_amdgcn_mfma_f32_32x32x16_bf16(kf[0][1], qr[0], f32x16{}, 0, 0, 0); }
;     else { c0 = __builtin_amdgcn_mfma_f32_32x32x16_bf16(kf[d0 & 1][0], qr[d0], c0, 0, 0, 0); c1 = __builtin_amdgcn_mfma_f32_32x32x16_bf16(kf[d0 & 1][1], qr[d0], c1, 0, 0, 0); }
;     if (d0 + 2 < NS) KRD_(d0 & 1, d0 + 2);
;     if constexpr (NOMAX) { }
;     else {
; #pragma unroll
;     for (int r = d0 * RPS; r < (d0 + 1) * RPS; ++r) { p1[r] = __builtin_amdgcn_exp2f(p1[r]); psa += p0[r]; }
;     if (d0 > 0) {
; #pragma unroll
;       for (int r = (d0 - 1) * RPS; r < d0 * RPS; ++r) psb += p1[r]; } }
;     if constexpr (NOMAX) {
;       if (d0 == NS / 4 - 1) { PK4R(p0, 0, pa[0]); PIN(pa[0]); }
;       if (d0 == NS / 2 - 1) { PK4R(p0, 8, pa[1]); PIN(pa[1]); }
;       if (d0 == 3 * NS / 4 - 1) { PK4R(p1, 0, pa[2]); PIN(pa[2]); }
;       if (d0 == NS - 1) { PK4R(p1, 8, pa[3]); PIN(pa[3]); }
;     } else {
;     if (d0 == NS / 2 - 1) { PK4R(p0, 0, pa[0]); PIN(pa[0]); }
;     if (d0 == NS / 2) { PK4R(p0, 8, pa[1]); PIN(pa[1]); }
;     if (d0 == NS - 1) { PK4R(p1, 0, pa[2]); PIN(pa[2]); }
;     }
;     if (d0 == NS - 1) {
;       vl[0] = vtr(vp + v_rd_off(0, 0, 0)); vh[0] = vtr(vp + v_rd_off(0, 0, 1)); vl[1] = vtr(vp + v_rd_off(1, 0, 0)); vh[1] = vtr(vp + v_rd_off(1, 0, 1)); }
;     PIN(p1); PIN(psa); PIN(psb);
;     SBAR();
;   }
.LBB0_325:
.LBB0_327:
	v_add_u32_e32 v212, s18, v207
	ds_read_b128 v[2:5], v212
	ds_read_b128 v[218:221], v212 offset:4096
	v_cvt_pk_bf16_f32 v128, v128, v129
	v_cvt_pk_bf16_f32 v129, v130, v131
	v_cvt_pk_bf16_f32 v130, v132, v133
	v_cvt_pk_bf16_f32 v131, v134, v135
	v_mfma_f32_32x32x16_bf16 v[80:95], v[84:87], v[156:159], 0
	v_permlane32_swap_b32_e32 v128, v130
	v_permlane32_swap_b32_e32 v129, v131
	v_mfma_f32_32x32x16_bf16 v[96:111], v[6:9], v[152:155], v[96:111]
	v_add_u32_e32 v6, s18, v208
	ds_read_b128 v[132:135], v6
	ds_read_b128 v[222:225], v6 offset:4096
	v_mfma_f32_32x32x16_bf16 v[80:95], v[10:13], v[152:155], v[80:95]
	v_cvt_pk_bf16_f32 v10, v136, v137
	v_cvt_pk_bf16_f32 v11, v138, v139
	v_cvt_pk_bf16_f32 v12, v140, v141
	v_cvt_pk_bf16_f32 v13, v142, v143
	s_nop 0
	v_permlane32_swap_b32_e32 v10, v12
	v_permlane32_swap_b32_e32 v11, v13
	s_waitcnt lgkmcnt(3)
	v_mfma_f32_32x32x16_bf16 v[96:111], v[2:5], v[148:151], v[96:111]
	v_cvt_pk_bf16_f32 v6, v112, v113
	v_cvt_pk_bf16_f32 v7, v114, v115
	v_cvt_pk_bf16_f32 v8, v116, v117
	v_cvt_pk_bf16_f32 v9, v118, v119
	s_nop 0
	v_permlane32_swap_b32_e32 v6, v8
	s_waitcnt lgkmcnt(2)
	v_mfma_f32_32x32x16_bf16 v[80:95], v[218:221], v[148:151], v[80:95]
	v_permlane32_swap_b32_e32 v7, v9
	s_nop 0
	v_cvt_pk_bf16_f32 v2, v120, v121
	v_cvt_pk_bf16_f32 v3, v122, v123
	v_cvt_pk_bf16_f32 v4, v124, v125
	v_cvt_pk_bf16_f32 v5, v126, v127
	s_waitcnt lgkmcnt(1)
	v_mfma_f32_32x32x16_bf16 v[96:111], v[132:135], v[144:147], v[96:111]
	v_permlane32_swap_b32_e32 v2, v4
	v_permlane32_swap_b32_e32 v3, v5
	s_cmp_gt_i32 s96, 60
	s_cbranch_scc1 .Lmy_mb0_a2_2
	s_waitcnt vmcnt(3) lgkmcnt(0)
	s_barrier

; template <int DK, bool NOMAX> ...
;     ...
;   if constexpr (NOMAX) { float ps = (psa + c0[15]) + (psb + c1[15]);
;     { auto rr = __builtin_amdgcn_permlane32_swap(__float_as_uint(ps), __float_as_uint(ps), false, false);
;       ps = __uint_as_float(rr[0]) + __uint_as_float(rr[1]); }
;     l_reg = l_reg * alpha + ps; }
.Lmy_resc_a2_1:
	s_nop 0
	v_add_f32_e32 v3, v143, v3
	v_add_f32_e32 v2, v127, v2
	v_add_f32_e32 v213, v3, v2
	v_mov_b32_e32 v214, v213
	s_nop 1
	v_permlane32_swap_b32_e32 v213, v214
	s_and_saveexec_b64 s[4:5], s[46:47]
	ds_write_b32 v188, v0 offset:128
	s_or_b64 exec, exec, s[4:5]
	s_waitcnt lgkmcnt(0)
	v_add_u32_e32 v96, s2, v170
	ds_read_b128 v[2:5], v96 offset:224
	ds_read_b128 v[88:91], v96 offset:192
	ds_read_b128 v[92:95], v96 offset:160
	ds_read_b128 v[96:99], v96 offset:128
	s_waitcnt lgkmcnt(0)
	v_pk_mul_f32 v[28:29], v[28:29], v[2:3]
	v_pk_mul_f32 v[24:25], v[24:25], v[88:89]
	v_pk_mul_f32 v[20:21], v[20:21], v[92:93]
	v_pk_mul_f32 v[30:31], v[30:31], v[4:5]
	v_pk_mul_f32 v[26:27], v[26:27], v[90:91]
	v_pk_mul_f32 v[22:23], v[22:23], v[94:95]
	v_pk_mul_f32 v[18:19], v[18:19], v[98:99]
	v_pk_mul_f32 v[16:17], v[16:17], v[96:97]
	v_pk_mul_f32 v[44:45], v[44:45], v[2:3]
	v_pk_mul_f32 v[40:41], v[40:41], v[88:89]
	v_pk_mul_f32 v[36:37], v[36:37], v[92:93]
	v_pk_mul_f32 v[46:47], v[46:47], v[4:5]
	v_pk_mul_f32 v[42:43], v[42:43], v[90:91]
	v_pk_mul_f32 v[38:39], v[38:39], v[94:95]
	v_pk_mul_f32 v[34:35], v[34:35], v[98:99]
	v_pk_mul_f32 v[32:33], v[32:33], v[96:97]
	v_pk_mul_f32 v[60:61], v[60:61], v[2:3]
	v_pk_mul_f32 v[56:57], v[56:57], v[88:89]
	v_pk_mul_f32 v[52:53], v[52:53], v[92:93]
	v_pk_mul_f32 v[62:63], v[62:63], v[4:5]
	v_pk_mul_f32 v[58:59], v[58:59], v[90:91]
	v_pk_mul_f32 v[54:55], v[54:55], v[94:95]
	v_pk_mul_f32 v[50:51], v[50:51], v[98:99]
	v_pk_mul_f32 v[48:49], v[48:49], v[96:97]
	v_pk_mul_f32 v[76:77], v[76:77], v[2:3]
	v_pk_mul_f32 v[72:73], v[72:73], v[88:89]
	v_pk_mul_f32 v[68:69], v[68:69], v[92:93]
	v_pk_mul_f32 v[78:79], v[78:79], v[4:5]
	v_pk_mul_f32 v[74:75], v[74:75], v[90:91]
	v_pk_mul_f32 v[70:71], v[70:71], v[94:95]
	v_pk_mul_f32 v[66:67], v[66:67], v[98:99]
	v_pk_mul_f32 v[64:65], v[64:65], v[96:97]
	s_waitcnt lgkmcnt(0)
	v_add_u32_e32 v217, s58, v187
	v_mfma_f32_32x32x16_bf16 v[96:111], v[80:83], v[156:159], 0
	s_branch .LBB0_323

; template <int DK, bool NOMAX> ...
;     ...
;   for (int i = 0; i < 16; ++i) {
;     if (i + 2 < 16) VRD_((i + 2) % 3, i + 2);
;     if (i == 1) { if (dk) __builtin_amdgcn_global_load_lds((const unsigned*)gk0, lk, 16, 0, 0); }
;     if (i == 3) { if constexpr (DK == 128) { if (dk) __builtin_amdgcn_global_load_lds((const unsigned*)gk1, (lds_up)((lds_cp)lk + 8192), 16, 0, 0); } }
;     if (i == 5) { if (dv) __builtin_amdgcn_global_load_lds((const unsigned*)gv0, lv, 16, 0, 0); }
;     if (i == 7) { if (dv) __builtin_amdgcn_global_load_lds((const unsigned*)gv1, (lds_up)((lds_cp)lv + 8192), 16, 0, 0); }
;     if (i == 12 || i == 13) { const int cb_ = ((i - 12) * 16 + hi * 8) * 2;
;       if constexpr (DK == 128) { kf[i - 12][0] = *reinterpret_cast<const bf16x8*>(Kn + KSWZ128(r32, cb_)); kf[i - 12][1] = *reinterpret_cast<const bf16x8*>(Kn + KSWZ128(32 + r32, cb_)); }
;       else { kf[i - 12][0] = *reinterpret_cast<const bf16x8*>(Kn + KSWZ64(r32, cb_)); kf[i - 12][1] = *reinterpret_cast<const bf16x8*>(Kn + KSWZ64(32 + r32, cb_)); } }
;     SBAR();
;     o[i & 3] = __builtin_amdgcn_mfma_f32_32x32x16_bf16(pa[i >> 2], VFR_(i % 3), o[i & 3], 0, 0, 0);
;     if constexpr (NOMAX) { c0[i] = __builtin_amdgcn_exp2f(c0[i]); c1[i] = __builtin_amdgcn_exp2f(c1[i]); if (i > 0) { psa += c0[i - 1]; psb += c1[i - 1]; } PIN(c0); PIN(c1); PIN(psa); PIN(psb); }
;     else {
;     if (i == 0) { ma = max3f(c0[0], c0[1], c1[0]); mb = max3f(c0[2], c0[3], c1[1]); ma = max3f(ma, c1[2], c1[3]); }
;     if (i >= 1 && i <= 3) { const int r = 4 * i; ma = max3f(ma, c0[r], c0[r + 1]); mb = max3f(mb, c0[r + 2], c0[r + 3]); ma = max3f(ma, c1[r], c1[r + 1]); mb = max3f(mb, c1[r + 2], c1[r + 3]); }
;     if (i == 4) { float pmax = fmaxf(ma, mb);
;       { auto rr = __builtin_amdgcn_permlane32_swap(__float_as_uint(pmax), __float_as_uint(pmax), false, false);
;         pmax = fmaxf(__uint_as_float(rr[0]), __uint_as_float(rr[1])); }
;       pmax += cb;
;       const bool keep = __all(pmax - m_reg <= THR2);
;       const float mn = keep ? m_reg : fmaxf(m_reg, pmax);
;       alpha = __builtin_amdgcn_exp2f(m_reg - mn); m_reg = mn; mnC = cb - mn; }
;     if (i >= 5 && i <= 8) { const int r = 4 * (i - 5);
; #pragma unroll
;       for (int q = 0; q < 4; ++q) { c0[r + q] += mnC; c1[r + q] += mnC; } }
;     if (i >= 9) { const int r0 = (i - 9) * 2 + (i > 14 ? 1 : 0), n = i >= 14 ? 3 : 2;
; #pragma unroll
.LBB0_406:
	s_and_b32 s10, s18, 0xc000
	s_add_i32 s12, s10, 0
	s_waitcnt lgkmcnt(4)
	v_mfma_f32_32x32x16_bf16 v[2:17], v[162:165], v[66:69], v[2:17]
	v_exp_f32_e32 v117, v117
	v_exp_f32_e32 v101, v101
	v_add_f32_e32 v79, v100, v79
	v_add_f32_e32 v78, v116, v78
	ds_read_b64_tr_b16 v[66:67], v0 offset:5120
	ds_read_b64_tr_b16 v[68:69], v0 offset:7168
	s_waitcnt lgkmcnt(4)
	v_mfma_f32_32x32x16_bf16 v[50:65], v[90:93], v[74:77], v[50:65]
	v_exp_f32_e32 v118, v118
	v_exp_f32_e32 v102, v102
	v_add_f32_e32 v79, v101, v79
	v_add_f32_e32 v78, v117, v78
	s_add_u32 vcc_lo, s0, s60
	s_addc_u32 vcc_hi, s1, s61
	s_add_i32 s10, s3, s16
	s_mov_b32 m0, s10
	ds_read_b64_tr_b16 v[74:75], v0 offset:5632
	ds_read_b64_tr_b16 v[76:77], v0 offset:7680
	global_load_lds_dwordx4 v172, vcc
	s_waitcnt lgkmcnt(4)
	v_mfma_f32_32x32x16_bf16 v[34:49], v[90:93], v[70:73], v[34:49]
	v_exp_f32_e32 v119, v119
	v_exp_f32_e32 v103, v103
	v_add_f32_e32 v79, v102, v79
	v_add_f32_e32 v78, v118, v78
	ds_read_b64_tr_b16 v[70:71], v0 offset:8192
	ds_read_b64_tr_b16 v[72:73], v0 offset:10240
	s_waitcnt lgkmcnt(4)
	v_mfma_f32_32x32x16_bf16 v[18:33], v[90:93], v[66:69], v[18:33]
	v_exp_f32_e32 v120, v120
	v_exp_f32_e32 v104, v104
	v_add_f32_e32 v79, v103, v79
	v_add_f32_e32 v78, v119, v78
	s_add_i32 m0, s10, 0x2000
	ds_read_b64_tr_b16 v[66:67], v0 offset:8704
	ds_read_b64_tr_b16 v[68:69], v0 offset:10752
	global_load_lds_dwordx4 v170, vcc
	s_waitcnt lgkmcnt(4)
	v_mfma_f32_32x32x16_bf16 v[2:17], v[90:93], v[74:77], v[2:17]
	v_exp_f32_e32 v121, v121
	v_exp_f32_e32 v105, v105
	v_add_f32_e32 v79, v104, v79
	v_add_f32_e32 v78, v120, v78
	ds_read_b64_tr_b16 v[74:75], v0 offset:9216
	ds_read_b64_tr_b16 v[76:77], v0 offset:11264
	s_waitcnt lgkmcnt(4)
	v_mfma_f32_32x32x16_bf16 v[50:65], v[86:89], v[70:73], v[50:65]
	v_exp_f32_e32 v122, v122
	v_exp_f32_e32 v106, v106
	v_add_f32_e32 v79, v105, v79
	v_add_f32_e32 v78, v121, v78
	ds_read_b64_tr_b16 v[70:71], v0 offset:9728
	ds_read_b64_tr_b16 v[72:73], v0 offset:11776
	s_waitcnt lgkmcnt(4)
	v_mfma_f32_32x32x16_bf16 v[34:49], v[86:89], v[66:69], v[34:49]
	v_exp_f32_e32 v123, v123
	v_exp_f32_e32 v107, v107
	v_add_f32_e32 v66, v106, v79
	v_add_f32_e32 v67, v122, v78
	ds_read_b64_tr_b16 v[78:79], v0 offset:12288
	ds_read_b64_tr_b16 v[80:81], v0 offset:14336
	s_waitcnt lgkmcnt(4)
	v_mfma_f32_32x32x16_bf16 v[18:33], v[86:89], v[74:77], v[18:33]
	v_exp_f32_e32 v124, v124
	v_exp_f32_e32 v108, v108
	v_add_f32_e32 v66, v107, v66
	v_add_f32_e32 v67, v123, v67
	ds_read_b64_tr_b16 v[74:75], v0 offset:12800
	ds_read_b64_tr_b16 v[76:77], v0 offset:14848
	s_waitcnt lgkmcnt(4)
	v_mfma_f32_32x32x16_bf16 v[2:17], v[86:89], v[70:73], v[2:17]
	v_exp_f32_e32 v125, v125
	v_exp_f32_e32 v109, v109
	v_add_f32_e32 v90, v108, v66
	v_add_f32_e32 v91, v124, v67
	v_add_u32_e32 v70, s12, v224
	ds_read_b64_tr_b16 v[86:87], v0 offset:13312
	ds_read_b64_tr_b16 v[88:89], v0 offset:15360
	ds_read_b128 v[66:69], v70
	ds_read_b128 v[70:73], v70 offset:8192
	s_waitcnt lgkmcnt(6)
	v_mfma_f32_32x32x16_bf16 v[50:65], v[82:85], v[78:81], v[50:65]
	v_exp_f32_e32 v126, v126
	v_exp_f32_e32 v110, v110
	v_add_f32_e32 v90, v109, v90
	v_add_f32_e32 v91, v125, v91
	ds_read_b64_tr_b16 v[78:79], v0 offset:13824
	ds_read_b64_tr_b16 v[80:81], v0 offset:15872
	v_add_u32_e32 v0, s12, v225
	ds_read_b128 v[162:165], v0
	ds_read_b128 v[166:169], v0 offset:8192
	s_waitcnt lgkmcnt(8)
	v_mfma_f32_32x32x16_bf16 v[34:49], v[82:85], v[74:77], v[34:49]
	v_exp_f32_e32 v127, v127
	v_exp_f32_e32 v111, v111
	v_add_f32_e32 v0, v110, v90
	v_add_f32_e32 v74, v126, v91
	s_waitcnt lgkmcnt(6)
	v_mfma_f32_32x32x16_bf16 v[18:33], v[82:85], v[86:89], v[18:33]
	v_exp_f32_e32 v128, v128
	v_exp_f32_e32 v112, v112
	v_add_f32_e32 v0, v111, v0
	v_add_f32_e32 v74, v127, v74
	s_waitcnt lgkmcnt(2)
	v_mfma_f32_32x32x16_bf16 v[2:17], v[82:85], v[78:81], v[2:17]
	v_exp_f32_e32 v129, v129
	v_exp_f32_e32 v113, v113
	v_add_f32_e32 v0, v112, v0
	v_add_f32_e32 v74, v128, v74
	s_waitcnt lgkmcnt(0)
	v_add_u32_e32 v227, s17, v204
	v_mfma_f32_32x32x16_bf16 v[82:97], v[66:69], v[158:161], 0
	s_nop 0
	v_add_f32_e32 v74, v129, v74
	v_add_f32_e32 v0, v113, v0
	v_add_f32_e32 v0, v74, v0
	v_mov_b32_e32 v226, v0
	s_nop 1
	v_permlane32_swap_b32_e32 v0, v226
	s_mov_b64 s[10:11], -1
; #define SBAR() __builtin_amdgcn_sched_barrier(0)
; __device__ __forceinline__ s16x4 vtr(lds_cptr p) { return __builtin_bit_cast(s16x4, __builtin_amdgcn_ds_read_tr16_b64_v4i16((__attribute__((address_space(3))) v4i16_t*)p)); }
; #define PIN(x) asm volatile("" : "+v"(x))
; template <int DK, bool NOMAX> ...
;     ...
;   float psa = 0.f, psb = 0.f;
;   SBAR();
; #pragma unroll
;   for (int d0 = 0; d0 < NS; ++d0) {
;     if (d0 == 0) { c0 = __builtin_amdgcn_mfma_f32_32x32x16_bf16(kf[0][0], qr[0], f32x16{}, 0, 0, 0); c1 = __builtin_amdgcn_mfma_f32_32x32x16_bf16(kf[0][1], qr[0], f32x16{}, 0, 0, 0); }
;     else { c0 = __builtin_amdgcn_mfma_f32_32x32x16_bf16(kf[d0 & 1][0], qr[d0], c0, 0, 0, 0); c1 = __builtin_amdgcn_mfma_f32_32x32x16_bf16(kf[d0 & 1][1], qr[d0], c1, 0, 0, 0); }
;     if (d0 + 2 < NS) KRD_(d0 & 1, d0 + 2);
;     if constexpr (NOMAX) { }
;     else {
; #pragma unroll
;     for (int r = d0 * RPS; r < (d0 + 1) * RPS; ++r) { p1[r] = __builtin_amdgcn_exp2f(p1[r]); psa += p0[r]; }
;     if (d0 > 0) {
; #pragma unroll
;       for (int r = (d0 - 1) * RPS; r < d0 * RPS; ++r) psb += p1[r]; } }
;     if constexpr (NOMAX) {
;       if (d0 == NS / 4 - 1) { PK4R(p0, 0, pa[0]); PIN(pa[0]); }
;       if (d0 == NS / 2 - 1) { PK4R(p0, 8, pa[1]); PIN(pa[1]); }
;       if (d0 == 3 * NS / 4 - 1) { PK4R(p1, 0, pa[2]); PIN(pa[2]); }
;       if (d0 == NS - 1) { PK4R(p1, 8, pa[3]); PIN(pa[3]); }
;     } else {
;     if (d0 == NS / 2 - 1) { PK4R(p0, 0, pa[0]); PIN(pa[0]); }
;     if (d0 == NS / 2) { PK4R(p0, 8, pa[1]); PIN(pa[1]); }
;     if (d0 == NS - 1) { PK4R(p1, 0, pa[2]); PIN(pa[2]); }
;     }
;     if (d0 == NS - 1) {
;       vl[0] = vtr(vp + v_rd_off(0, 0, 0)); vh[0] = vtr(vp + v_rd_off(0, 0, 1)); vl[1] = vtr(vp + v_rd_off(1, 0, 0)); vh[1] = vtr(vp + v_rd_off(1, 0, 1)); }
;     PIN(p1); PIN(psa); PIN(psb);
;     SBAR();
;   }
.LBB0_408:
.LBB0_410:
	v_add_u32_e32 v232, s12, v218
	ds_read_b128 v[228:231], v232
	ds_read_b128 v[232:235], v232 offset:8192
	v_mfma_f32_32x32x16_bf16 v[66:81], v[70:73], v[158:161], 0
	v_mfma_f32_32x32x16_bf16 v[82:97], v[162:165], v[154:157], v[82:97]
	v_add_u32_e32 v162, s12, v219
	v_mfma_f32_32x32x16_bf16 v[66:81], v[166:169], v[154:157], v[66:81]
	ds_read_b128 v[166:169], v162
	ds_read_b128 v[236:239], v162 offset:8192
	v_cvt_pk_bf16_f32 v162, v114, v115
	v_cvt_pk_bf16_f32 v163, v116, v117
	v_cvt_pk_bf16_f32 v164, v118, v119
	v_cvt_pk_bf16_f32 v165, v120, v121
	s_nop 0
	v_permlane32_swap_b32_e32 v162, v164
	v_permlane32_swap_b32_e32 v163, v165
	s_waitcnt lgkmcnt(3)
	v_mfma_f32_32x32x16_bf16 v[82:97], v[228:231], v[150:153], v[82:97]
	v_add_u32_e32 v118, s12, v220
	ds_read_b128 v[114:117], v118
	ds_read_b128 v[118:121], v118 offset:8192
	s_waitcnt lgkmcnt(4)
	v_mfma_f32_32x32x16_bf16 v[66:81], v[232:235], v[150:153], v[66:81]
	s_waitcnt lgkmcnt(3)
	v_mfma_f32_32x32x16_bf16 v[82:97], v[166:169], v[146:149], v[82:97]
	v_add_u32_e32 v228, s12, v221
	ds_read_b128 v[166:169], v228
	ds_read_b128 v[228:231], v228 offset:8192
	v_cvt_pk_bf16_f32 v122, v122, v123
	v_cvt_pk_bf16_f32 v123, v124, v125
	v_cvt_pk_bf16_f32 v124, v126, v127
	v_cvt_pk_bf16_f32 v125, v128, v129
	s_waitcnt lgkmcnt(4)
	v_mfma_f32_32x32x16_bf16 v[66:81], v[236:239], v[146:149], v[66:81]
	v_permlane32_swap_b32_e32 v122, v124
	v_permlane32_swap_b32_e32 v123, v125
	s_waitcnt lgkmcnt(3)
	v_mfma_f32_32x32x16_bf16 v[82:97], v[114:117], v[142:145], v[82:97]
	s_waitcnt lgkmcnt(2)
	v_mfma_f32_32x32x16_bf16 v[66:81], v[118:121], v[142:145], v[66:81]
	v_add_u32_e32 v118, s12, v222
	ds_read_b128 v[114:117], v118
	ds_read_b128 v[126:129], v118 offset:8192
	s_waitcnt lgkmcnt(3)
	v_mfma_f32_32x32x16_bf16 v[82:97], v[166:169], v[138:141], v[82:97]
	v_add_u32_e32 v118, s12, v223
	s_waitcnt lgkmcnt(2)
	v_mfma_f32_32x32x16_bf16 v[66:81], v[228:231], v[138:141], v[66:81]
	ds_read_b128 v[166:169], v118
	ds_read_b128 v[228:231], v118 offset:8192
	v_cvt_pk_bf16_f32 v118, v98, v99
	v_cvt_pk_bf16_f32 v119, v100, v101
	v_cvt_pk_bf16_f32 v120, v102, v103
	v_cvt_pk_bf16_f32 v121, v104, v105
	s_nop 0
	v_permlane32_swap_b32_e32 v118, v120
	v_permlane32_swap_b32_e32 v119, v121
	s_waitcnt lgkmcnt(3)
	v_mfma_f32_32x32x16_bf16 v[82:97], v[114:117], v[130:133], v[82:97]
	s_waitcnt lgkmcnt(2)
	v_mfma_f32_32x32x16_bf16 v[66:81], v[126:129], v[130:133], v[66:81]
	v_cvt_pk_bf16_f32 v114, v106, v107
	v_cvt_pk_bf16_f32 v115, v108, v109
	v_cvt_pk_bf16_f32 v116, v110, v111
	v_cvt_pk_bf16_f32 v117, v112, v113
	s_waitcnt lgkmcnt(1)
	v_mfma_f32_32x32x16_bf16 v[82:97], v[166:169], v[134:137], v[82:97]
	v_permlane32_swap_b32_e32 v114, v116
	v_permlane32_swap_b32_e32 v115, v117
	s_cmpk_gt_i32 s15, 0x7c
	s_cbranch_scc1 .Lmy_mb0_b1_2
	s_waitcnt vmcnt(4) lgkmcnt(0)
	s_barrier

; #define SBAR() __builtin_amdgcn_sched_barrier(0)
; __device__ __forceinline__ s16x4 vtr(lds_cptr p) { return __builtin_bit_cast(s16x4, __builtin_amdgcn_ds_read_tr16_b64_v4i16((__attribute__((address_space(3))) v4i16_t*)p)); }
; #define PIN(x) asm volatile("" : "+v"(x))
; template <int DK, bool NOMAX> ...
;     ...
;   float psa = 0.f, psb = 0.f;
;   SBAR();
; #pragma unroll
;   for (int d0 = 0; d0 < NS; ++d0) {
;     if (d0 == 0) { c0 = __builtin_amdgcn_mfma_f32_32x32x16_bf16(kf[0][0], qr[0], f32x16{}, 0, 0, 0); c1 = __builtin_amdgcn_mfma_f32_32x32x16_bf16(kf[0][1], qr[0], f32x16{}, 0, 0, 0); }
;     else { c0 = __builtin_amdgcn_mfma_f32_32x32x16_bf16(kf[d0 & 1][0], qr[d0], c0, 0, 0, 0); c1 = __builtin_amdgcn_mfma_f32_32x32x16_bf16(kf[d0 & 1][1], qr[d0], c1, 0, 0, 0); }
;     if (d0 + 2 < NS) KRD_(d0 & 1, d0 + 2);
;     if constexpr (NOMAX) { }
;     else {
; #pragma unroll
;     for (int r = d0 * RPS; r < (d0 + 1) * RPS; ++r) { p1[r] = __builtin_amdgcn_exp2f(p1[r]); psa += p0[r]; }
;     if (d0 > 0) {
; #pragma unroll
;       for (int r = (d0 - 1) * RPS; r < d0 * RPS; ++r) psb += p1[r]; } }
;     if constexpr (NOMAX) {
;       if (d0 == NS / 4 - 1) { PK4R(p0, 0, pa[0]); PIN(pa[0]); }
;       if (d0 == NS / 2 - 1) { PK4R(p0, 8, pa[1]); PIN(pa[1]); }
;       if (d0 == 3 * NS / 4 - 1) { PK4R(p1, 0, pa[2]); PIN(pa[2]); }
;       if (d0 == NS - 1) { PK4R(p1, 8, pa[3]); PIN(pa[3]); }
;     } else {
;     if (d0 == NS / 2 - 1) { PK4R(p0, 0, pa[0]); PIN(pa[0]); }
;     if (d0 == NS / 2) { PK4R(p0, 8, pa[1]); PIN(pa[1]); }
;     if (d0 == NS - 1) { PK4R(p1, 0, pa[2]); PIN(pa[2]); }
;     }
;     if (d0 == NS - 1) {
;       vl[0] = vtr(vp + v_rd_off(0, 0, 0)); vh[0] = vtr(vp + v_rd_off(0, 0, 1)); vl[1] = vtr(vp + v_rd_off(1, 0, 0)); vh[1] = vtr(vp + v_rd_off(1, 0, 1)); }
;     PIN(p1); PIN(psa); PIN(psb);
;     SBAR();
;   }
.LBB0_468:
.LBB0_470:
	v_add_u32_e32 v232, s12, v218
	ds_read_b128 v[228:231], v232
	ds_read_b128 v[232:235], v232 offset:8192
	v_mfma_f32_32x32x16_bf16 v[66:81], v[70:73], v[158:161], 0
	v_mfma_f32_32x32x16_bf16 v[82:97], v[162:165], v[154:157], v[82:97]
	v_add_u32_e32 v162, s12, v219
	v_mfma_f32_32x32x16_bf16 v[66:81], v[166:169], v[154:157], v[66:81]
	ds_read_b128 v[166:169], v162
	ds_read_b128 v[236:239], v162 offset:8192
	v_cvt_pk_bf16_f32 v162, v114, v115
	v_cvt_pk_bf16_f32 v163, v116, v117
	v_cvt_pk_bf16_f32 v164, v118, v119
	v_cvt_pk_bf16_f32 v165, v120, v121
	s_nop 0
	v_permlane32_swap_b32_e32 v162, v164
	v_permlane32_swap_b32_e32 v163, v165
	s_waitcnt lgkmcnt(3)
	v_mfma_f32_32x32x16_bf16 v[82:97], v[228:231], v[150:153], v[82:97]
	v_add_u32_e32 v118, s12, v220
	ds_read_b128 v[114:117], v118
	ds_read_b128 v[118:121], v118 offset:8192
	s_waitcnt lgkmcnt(4)
	v_mfma_f32_32x32x16_bf16 v[66:81], v[232:235], v[150:153], v[66:81]
	s_waitcnt lgkmcnt(3)
	v_mfma_f32_32x32x16_bf16 v[82:97], v[166:169], v[146:149], v[82:97]
	v_add_u32_e32 v228, s12, v221
	ds_read_b128 v[166:169], v228
	ds_read_b128 v[228:231], v228 offset:8192
	v_cvt_pk_bf16_f32 v122, v122, v123
	v_cvt_pk_bf16_f32 v123, v124, v125
	v_cvt_pk_bf16_f32 v124, v126, v127
	v_cvt_pk_bf16_f32 v125, v128, v129
	s_waitcnt lgkmcnt(4)
	v_mfma_f32_32x32x16_bf16 v[66:81], v[236:239], v[146:149], v[66:81]
	v_permlane32_swap_b32_e32 v122, v124
	v_permlane32_swap_b32_e32 v123, v125
	s_waitcnt lgkmcnt(3)
	v_mfma_f32_32x32x16_bf16 v[82:97], v[114:117], v[142:145], v[82:97]
	s_waitcnt lgkmcnt(2)
	v_mfma_f32_32x32x16_bf16 v[66:81], v[118:121], v[142:145], v[66:81]
	v_add_u32_e32 v118, s12, v222
	ds_read_b128 v[114:117], v118
	ds_read_b128 v[126:129], v118 offset:8192
	s_waitcnt lgkmcnt(3)
	v_mfma_f32_32x32x16_bf16 v[82:97], v[166:169], v[138:141], v[82:97]
	v_add_u32_e32 v118, s12, v223
	s_waitcnt lgkmcnt(2)
	v_mfma_f32_32x32x16_bf16 v[66:81], v[228:231], v[138:141], v[66:81]
	ds_read_b128 v[166:169], v118
	ds_read_b128 v[228:231], v118 offset:8192
	v_cvt_pk_bf16_f32 v118, v98, v99
	v_cvt_pk_bf16_f32 v119, v100, v101
	v_cvt_pk_bf16_f32 v120, v102, v103
	v_cvt_pk_bf16_f32 v121, v104, v105
	s_nop 0
	v_permlane32_swap_b32_e32 v118, v120
	v_permlane32_swap_b32_e32 v119, v121
	s_waitcnt lgkmcnt(3)
	v_mfma_f32_32x32x16_bf16 v[82:97], v[114:117], v[130:133], v[82:97]
	s_waitcnt lgkmcnt(2)
	v_mfma_f32_32x32x16_bf16 v[66:81], v[126:129], v[130:133], v[66:81]
	v_cvt_pk_bf16_f32 v114, v106, v107
	v_cvt_pk_bf16_f32 v115, v108, v109
	v_cvt_pk_bf16_f32 v116, v110, v111
	v_cvt_pk_bf16_f32 v117, v112, v113
	s_waitcnt lgkmcnt(1)
	v_mfma_f32_32x32x16_bf16 v[82:97], v[166:169], v[134:137], v[82:97]
	v_permlane32_swap_b32_e32 v114, v116
	v_permlane32_swap_b32_e32 v115, v117
	s_cmp_gt_i32 s14, 60
	s_cbranch_scc1 .Lmy_mb0_b2_2
	s_waitcnt vmcnt(4) lgkmcnt(0)
	s_barrier
